# grid barrier: acquire-side invalidate issued right after the arrival ticket returns so it overlaps the leader's L2 write-back rather than the ticket round trip
# speedup vs baseline: 1.0043x; 1.0043x over previous
; __device__ __forceinline__ unsigned xb_ld(unsigned* p)              { return __hip_atomic_load(p, __ATOMIC_RELAXED, __HIP_MEMORY_SCOPE_AGENT); }
; __device__ __forceinline__ unsigned xb_add(unsigned* p, unsigned v) { return __hip_atomic_fetch_add(p, v, __ATOMIC_RELAXED, __HIP_MEMORY_SCOPE_AGENT); }
; #define XB_SPIN(cond, bar) do { unsigned _sp = 0; while (cond) { __builtin_amdgcn_s_sleep(1); \
;     if ((++_sp & 255u) == 0u) { if (xb_ld(&(bar)[XB_TMO])) break; if (_sp > XB_SPIN_CAP) { atomicAdd(&(bar)[XB_TMO], 1u); break; } } } } while (0)
; __device__ __forceinline__ void xcd_barrier(const XcdBarrier& b) {
;     ...
;         const unsigned old = xb_add(&bar[XB_XSUB(b.x)], 1u);
;         const unsigned gen = old / nloc;
;         if (old + 1u == (gen + 1u) * nloc) {
;             __builtin_amdgcn_fence(__ATOMIC_RELEASE, "agent");
;             asm volatile("s_waitcnt vmcnt(0)" ::: "memory");
;             const unsigned og = xb_add(&bar[XB_TOP], 1u);
;             const unsigned tg = og / nx;
;             if (og + 1u == (tg + 1u) * nx) xb_add(&bar[XB_TOPGEN], 1u);
;             else XB_SPIN(xb_ld(&bar[XB_TOPGEN]) == tg, bar);
;             __builtin_amdgcn_fence(__ATOMIC_ACQUIRE, "agent");
.LBB0_120:
	s_or_b64 exec, exec, s[12:13]
	v_cvt_f32_u32_e32 v4, v2
	s_waitcnt vmcnt(0)
	buffer_inv sc1
	v_readfirstlane_b32 s3, v3
	v_sub_u32_e32 v3, 0, v2
	v_rcp_iflag_f32_e32 v4, v4
	v_add_u32_e32 v5, s3, v1
	v_mul_f32_e32 v4, 0x4f7ffffe, v4
	v_cvt_u32_f32_e32 v4, v4
	v_mul_lo_u32 v1, v3, v4
	v_mul_hi_u32 v1, v4, v1
	v_add_u32_e32 v1, v4, v1
	v_mul_hi_u32 v1, v5, v1
	v_mul_lo_u32 v3, v1, v2
	v_sub_u32_e32 v3, v5, v3
	v_add_u32_e32 v4, 1, v1
	v_cmp_ge_u32_e32 vcc, v3, v2
	s_nop 1
	v_cndmask_b32_e32 v1, v1, v4, vcc
	v_sub_u32_e32 v4, v3, v2
	v_cndmask_b32_e32 v3, v3, v4, vcc
	v_add_u32_e32 v4, 1, v1
	v_cmp_ge_u32_e32 vcc, v3, v2
	v_add_u32_e32 v3, 1, v5
	s_nop 0
	v_cndmask_b32_e32 v1, v1, v4, vcc
	v_mul_lo_u32 v4, v2, v1
	v_add_u32_e32 v2, v4, v2
	v_cmp_ne_u32_e32 vcc, v3, v2
	s_and_saveexec_b64 s[10:11], vcc
	s_xor_b64 s[10:11], exec, s[10:11]
	s_cbranch_execz .LBB0_134
	s_waitcnt lgkmcnt(0)
	v_add_u32_e32 v16, 1, v1
	v_mul_lo_u32 v16, v16, v0
	v_mov_b32_e32 v0, 0
	s_add_u32 s16, s6, 0x2e803400
	s_addc_u32 s17, s7, 0
	global_load_dword v0, v0, s[16:17] sc1
	s_waitcnt vmcnt(0)
	v_cmp_lt_u32_e32 vcc, v0, v16
	s_and_saveexec_b64 s[12:13], vcc
	s_cbranch_execz .LBB0_133
	s_add_u32 s14, s6, 0x2e800200
	s_addc_u32 s15, s7, 0
	s_mov_b32 s3, 1
	s_mov_b64 s[18:19], 0
	v_mov_b32_e32 v0, 0
	s_branch .LBB0_124

; __device__ __forceinline__ unsigned xb_ld(unsigned* p)              { return __hip_atomic_load(p, __ATOMIC_RELAXED, __HIP_MEMORY_SCOPE_AGENT); }
; __device__ __forceinline__ unsigned xb_add(unsigned* p, unsigned v) { return __hip_atomic_fetch_add(p, v, __ATOMIC_RELAXED, __HIP_MEMORY_SCOPE_AGENT); }
; #define XB_SPIN(cond, bar) do { unsigned _sp = 0; while (cond) { __builtin_amdgcn_s_sleep(1); \
;     if ((++_sp & 255u) == 0u) { if (xb_ld(&(bar)[XB_TMO])) break; if (_sp > XB_SPIN_CAP) { atomicAdd(&(bar)[XB_TMO], 1u); break; } } } } while (0)
; __device__ __forceinline__ void xcd_barrier(const XcdBarrier& b) {
;     ...
;         const unsigned old = xb_add(&bar[XB_XSUB(b.x)], 1u);
;         const unsigned gen = old / nloc;
;         if (old + 1u == (gen + 1u) * nloc) {
;             __builtin_amdgcn_fence(__ATOMIC_RELEASE, "agent");
;             asm volatile("s_waitcnt vmcnt(0)" ::: "memory");
;             const unsigned og = xb_add(&bar[XB_TOP], 1u);
;             const unsigned tg = og / nx;
;             if (og + 1u == (tg + 1u) * nx) xb_add(&bar[XB_TOPGEN], 1u);
;             else XB_SPIN(xb_ld(&bar[XB_TOPGEN]) == tg, bar);
;             __builtin_amdgcn_fence(__ATOMIC_ACQUIRE, "agent");
.LBB0_206:
	s_or_b64 exec, exec, s[12:13]
	v_cvt_f32_u32_e32 v4, v2
	s_waitcnt vmcnt(0)
	buffer_inv sc1
	v_readfirstlane_b32 s3, v3
	v_sub_u32_e32 v3, 0, v2
	v_rcp_iflag_f32_e32 v4, v4
	v_add_u32_e32 v5, s3, v1
	v_mul_f32_e32 v4, 0x4f7ffffe, v4
	v_cvt_u32_f32_e32 v4, v4
	v_mul_lo_u32 v1, v3, v4
	v_mul_hi_u32 v1, v4, v1
	v_add_u32_e32 v1, v4, v1
	v_mul_hi_u32 v1, v5, v1
	v_mul_lo_u32 v3, v1, v2
	v_sub_u32_e32 v3, v5, v3
	v_add_u32_e32 v4, 1, v1
	v_cmp_ge_u32_e32 vcc, v3, v2
	s_nop 1
	v_cndmask_b32_e32 v1, v1, v4, vcc
	v_sub_u32_e32 v4, v3, v2
	v_cndmask_b32_e32 v3, v3, v4, vcc
	v_add_u32_e32 v4, 1, v1
	v_cmp_ge_u32_e32 vcc, v3, v2
	v_add_u32_e32 v3, 1, v5
	s_nop 0
	v_cndmask_b32_e32 v1, v1, v4, vcc
	v_mul_lo_u32 v4, v2, v1
	v_add_u32_e32 v2, v4, v2
	v_cmp_ne_u32_e32 vcc, v3, v2
	s_and_saveexec_b64 s[10:11], vcc
	s_xor_b64 s[10:11], exec, s[10:11]
	s_cbranch_execz .LBB0_220
	s_waitcnt lgkmcnt(0)
	v_add_u32_e32 v16, 1, v1
	v_mul_lo_u32 v16, v16, v0
	s_add_u32 s16, s6, 0x2e803400
	s_addc_u32 s17, s7, 0
	global_load_dword v0, v97, s[16:17] sc1
	s_waitcnt vmcnt(0)
	v_cmp_lt_u32_e32 vcc, v0, v16
	s_and_saveexec_b64 s[12:13], vcc
	s_cbranch_execz .LBB0_219
	s_add_u32 s14, s6, 0x2e800200
	s_addc_u32 s15, s7, 0
	s_mov_b32 s3, 1
	s_mov_b64 s[34:35], 0
	s_branch .LBB0_210

; __device__ __forceinline__ unsigned xb_ld(unsigned* p)              { return __hip_atomic_load(p, __ATOMIC_RELAXED, __HIP_MEMORY_SCOPE_AGENT); }
; __device__ __forceinline__ unsigned xb_add(unsigned* p, unsigned v) { return __hip_atomic_fetch_add(p, v, __ATOMIC_RELAXED, __HIP_MEMORY_SCOPE_AGENT); }
; #define XB_SPIN(cond, bar) do { unsigned _sp = 0; while (cond) { __builtin_amdgcn_s_sleep(1); \
;     if ((++_sp & 255u) == 0u) { if (xb_ld(&(bar)[XB_TMO])) break; if (_sp > XB_SPIN_CAP) { atomicAdd(&(bar)[XB_TMO], 1u); break; } } } } while (0)
; __device__ __forceinline__ void xcd_barrier(const XcdBarrier& b) {
;     ...
;         const unsigned old = xb_add(&bar[XB_XSUB(b.x)], 1u);
;         const unsigned gen = old / nloc;
;         if (old + 1u == (gen + 1u) * nloc) {
;             __builtin_amdgcn_fence(__ATOMIC_RELEASE, "agent");
;             asm volatile("s_waitcnt vmcnt(0)" ::: "memory");
;             const unsigned og = xb_add(&bar[XB_TOP], 1u);
;             const unsigned tg = og / nx;
;             if (og + 1u == (tg + 1u) * nx) xb_add(&bar[XB_TOPGEN], 1u);
;             else XB_SPIN(xb_ld(&bar[XB_TOPGEN]) == tg, bar);
;             __builtin_amdgcn_fence(__ATOMIC_ACQUIRE, "agent");
.LBB0_306:
	s_or_b64 exec, exec, s[12:13]
	v_cvt_f32_u32_e32 v4, v2
	s_waitcnt vmcnt(0)
	buffer_inv sc1
	v_readfirstlane_b32 s2, v3
	v_sub_u32_e32 v3, 0, v2
	v_rcp_iflag_f32_e32 v4, v4
	v_add_u32_e32 v5, s2, v1
	v_mul_f32_e32 v4, 0x4f7ffffe, v4
	v_cvt_u32_f32_e32 v4, v4
	v_mul_lo_u32 v1, v3, v4
	v_mul_hi_u32 v1, v4, v1
	v_add_u32_e32 v1, v4, v1
	v_mul_hi_u32 v1, v5, v1
	v_mul_lo_u32 v3, v1, v2
	v_sub_u32_e32 v3, v5, v3
	v_add_u32_e32 v4, 1, v1
	v_cmp_ge_u32_e32 vcc, v3, v2
	s_nop 1
	v_cndmask_b32_e32 v1, v1, v4, vcc
	v_sub_u32_e32 v4, v3, v2
	v_cndmask_b32_e32 v3, v3, v4, vcc
	v_add_u32_e32 v4, 1, v1
	v_cmp_ge_u32_e32 vcc, v3, v2
	v_add_u32_e32 v3, 1, v5
	s_nop 0
	v_cndmask_b32_e32 v1, v1, v4, vcc
	v_mul_lo_u32 v4, v2, v1
	v_add_u32_e32 v2, v4, v2
	v_cmp_ne_u32_e32 vcc, v3, v2
	s_and_saveexec_b64 s[2:3], vcc
	s_xor_b64 s[10:11], exec, s[2:3]
	s_cbranch_execz .LBB0_320
	s_waitcnt lgkmcnt(0)
	v_add_u32_e32 v16, 1, v1
	v_mul_lo_u32 v16, v16, v0
	s_add_u32 s16, s6, 0x2e803400
	s_addc_u32 s17, s7, 0
	global_load_dword v0, v97, s[16:17] sc1
	s_waitcnt vmcnt(0)
	v_cmp_lt_u32_e32 vcc, v0, v16
	s_and_saveexec_b64 s[12:13], vcc
	s_cbranch_execz .LBB0_319
	s_add_u32 s14, s6, 0x2e800200
	s_addc_u32 s15, s7, 0
	s_mov_b32 s2, 1
	s_mov_b64 s[34:35], 0
	s_branch .LBB0_310

; __device__ __forceinline__ unsigned xb_ld(unsigned* p)              { return __hip_atomic_load(p, __ATOMIC_RELAXED, __HIP_MEMORY_SCOPE_AGENT); }
; __device__ __forceinline__ unsigned xb_add(unsigned* p, unsigned v) { return __hip_atomic_fetch_add(p, v, __ATOMIC_RELAXED, __HIP_MEMORY_SCOPE_AGENT); }
; #define XB_SPIN(cond, bar) do { unsigned _sp = 0; while (cond) { __builtin_amdgcn_s_sleep(1); \
;     if ((++_sp & 255u) == 0u) { if (xb_ld(&(bar)[XB_TMO])) break; if (_sp > XB_SPIN_CAP) { atomicAdd(&(bar)[XB_TMO], 1u); break; } } } } while (0)
; __device__ __forceinline__ void xcd_barrier(const XcdBarrier& b) {
;     ...
;         const unsigned old = xb_add(&bar[XB_XSUB(b.x)], 1u);
;         const unsigned gen = old / nloc;
;         if (old + 1u == (gen + 1u) * nloc) {
;             __builtin_amdgcn_fence(__ATOMIC_RELEASE, "agent");
;             asm volatile("s_waitcnt vmcnt(0)" ::: "memory");
;             const unsigned og = xb_add(&bar[XB_TOP], 1u);
;             const unsigned tg = og / nx;
;             if (og + 1u == (tg + 1u) * nx) xb_add(&bar[XB_TOPGEN], 1u);
;             else XB_SPIN(xb_ld(&bar[XB_TOPGEN]) == tg, bar);
;             __builtin_amdgcn_fence(__ATOMIC_ACQUIRE, "agent");
.LBB0_672:
	s_or_b64 exec, exec, s[14:15]
	v_cvt_f32_u32_e32 v4, v2
	s_waitcnt vmcnt(0)
	buffer_inv sc1
	v_readfirstlane_b32 s3, v3
	v_sub_u32_e32 v3, 0, v2
	v_rcp_iflag_f32_e32 v4, v4
	v_add_u32_e32 v5, s3, v1
	v_mul_f32_e32 v4, 0x4f7ffffe, v4
	v_cvt_u32_f32_e32 v4, v4
	v_mul_lo_u32 v1, v3, v4
	v_mul_hi_u32 v1, v4, v1
	v_add_u32_e32 v1, v4, v1
	v_mul_hi_u32 v1, v5, v1
	v_mul_lo_u32 v3, v1, v2
	v_sub_u32_e32 v3, v5, v3
	v_add_u32_e32 v4, 1, v1
	v_cmp_ge_u32_e32 vcc, v3, v2
	s_nop 1
	v_cndmask_b32_e32 v1, v1, v4, vcc
	v_sub_u32_e32 v4, v3, v2
	v_cndmask_b32_e32 v3, v3, v4, vcc
	v_add_u32_e32 v4, 1, v1
	v_cmp_ge_u32_e32 vcc, v3, v2
	v_add_u32_e32 v3, 1, v5
	s_nop 0
	v_cndmask_b32_e32 v1, v1, v4, vcc
	v_mul_lo_u32 v4, v2, v1
	v_add_u32_e32 v2, v4, v2
	v_cmp_ne_u32_e32 vcc, v3, v2
	s_and_saveexec_b64 s[10:11], vcc
	s_xor_b64 s[10:11], exec, s[10:11]
	s_cbranch_execz .LBB0_703
	s_waitcnt lgkmcnt(0)
	v_add_u32_e32 v16, 1, v1
	v_mul_lo_u32 v16, v16, v0
	s_add_u32 s34, s6, 0x2e803400
	s_addc_u32 s35, s7, 0
	global_load_dword v0, v97, s[34:35] sc1
	s_waitcnt vmcnt(0)
	v_cmp_lt_u32_e32 vcc, v0, v16
	s_and_saveexec_b64 s[14:15], vcc
	s_cbranch_execz .LBB0_702
	s_add_u32 s16, s6, 0x2e800200
	s_addc_u32 s17, s7, 0
	s_mov_b32 s3, 1
	s_mov_b64 s[52:53], 0
	s_branch .LBB0_676
